# cmp1 items moved from workgroups 0..127 (3 nsa_q tiles) to 128..255 (2 nsa_q tiles): same items, balanced phase
# speedup vs baseline: 1.0038x; 1.0038x over previous
.LBB0_2139:
	s_cmp_lt_i32 s18, s20
	s_cselect_b64 s[2:3], -1, 0
	s_xor_b64 s[0:1], s[0:1], -1
	s_or_b64 s[0:1], s[2:3], s[0:1]
	s_and_b64 vcc, exec, s[0:1]
	s_cbranch_vccnz .LBB0_2142
	v_readlane_b32 s0, v250, 60
	v_readlane_b32 s1, v250, 61
	s_andn2_b64 vcc, exec, s[0:1]
	v_readlane_b32 s0, v251, 21
	v_readlane_b32 s52, v249, 26
	v_readlane_b32 s6, v251, 23
	s_mov_b32 s7, s0
	v_readlane_b32 s53, v249, 27
	v_readlane_b32 s54, v249, 28
	v_readlane_b32 s55, v249, 29
	v_readlane_b32 s56, v249, 30
	v_readlane_b32 s57, v249, 31
	v_readlane_b32 s58, v249, 32
	v_readlane_b32 s59, v249, 33
	v_readlane_b32 s60, v249, 34
	v_readlane_b32 s61, v249, 35
	v_readlane_b32 s62, v249, 36
	v_readlane_b32 s63, v249, 37
	v_readlane_b32 s64, v249, 38
	v_readlane_b32 s65, v249, 39
	v_readlane_b32 s66, v249, 40
	v_readlane_b32 s67, v249, 41
	v_readlane_b32 s1, v251, 22
	s_add_i32 s100, s7, 0xffffff80
	s_cmp_lt_u32 s100, 0x80
	s_cbranch_scc0 .LBB0_2141
	s_mov_b32 s7, s100
	s_add_i32 s6, s6, 0xffffc000
	s_branch .LBB0_2159
